# w_down conversion items re-split: first 768 of 2816 done by the gate/up (early) group after its gate/up items, the rest by the late group
# speedup vs baseline: 1.0051x; 1.0051x over previous
.Lcv_chain_wd:
	v_and_b32_e32 v110, 63, v252
	v_lshrrev_b32_e32 v0, 6, v252
	v_writelane_b32 v111, s16, 0
	v_writelane_b32 v111, s17, 1
	v_writelane_b32 v111, s18, 2
	v_writelane_b32 v111, s19, 3
	v_writelane_b32 v111, s20, 4
	v_writelane_b32 v111, s21, 5
	v_writelane_b32 v111, s22, 6
	v_writelane_b32 v111, s23, 7
	v_writelane_b32 v111, s24, 8
	v_writelane_b32 v111, s25, 9
	v_writelane_b32 v111, s26, 10
	v_writelane_b32 v111, s27, 11
	v_readfirstlane_b32 s0, v0
	s_mul_i32 s1, s0, 0x4100
	s_sub_i32 s16, s2, 0x80
	s_lshl_b32 s16, s16, 3
	s_add_u32 s16, s16, s0
	s_cmp_lt_u32 s16, 0x300
	s_cbranch_scc0 .Lcv_wde_skip
	v_lshrrev_b32_e32 v0, 4, v110
	v_and_b32_e32 v1, 15, v110
	v_and_b32_e32 v2, 7, v110
	v_lshrrev_b32_e32 v3, 3, v110
	v_mul_u32_u24_e32 v64, 0x2000, v0
	v_lshl_add_u32 v64, v1, 4, v64
	v_mul_u32_u24_e32 v65, 0x104, v0
	v_lshl_add_u32 v65, v1, 4, v65
	v_add_u32_e32 v65, s1, v65
	v_mul_u32_u24_e32 v66, 0x820, v2
	v_lshl_add_u32 v66, v3, 2, v66
	v_add_u32_e32 v66, s1, v66
	v_add_u32_e32 v67, 0x410, v66
	v_mul_u32_u24_e32 v68, 0x2c00, v3
	v_lshl_add_u32 v68, v2, 4, v68
	v_mov_b32_e32 v4, 0x23fa0
	ds_read_b64 v[0:1], v4
	s_waitcnt lgkmcnt(0)
	v_readfirstlane_b32 s18, v0
	v_readfirstlane_b32 s19, v1
	s_add_u32 s26, s54, 0x4800000
	s_addc_u32 s27, s55, 0
	s_nop 4
	s_lshr_b32 s98, s16, 5
	s_and_b32 s99, s16, 31
	s_lshl_b32 s0, s98, 19
	s_lshl_b32 s100, s99, 8
	s_add_u32 s0, s0, s100
	s_add_u32 s4, s18, s0
	s_addc_u32 s5, s19, 0
	s_mul_i32 s0, s99, 0xb0000
	s_lshl_b32 s100, s98, 7
	s_add_u32 s0, s0, s100
	s_add_u32 s24, s26, s0
	s_addc_u32 s25, s27, 0
	global_load_dwordx4 v[0:3], v64, s[4:5] nt
	s_add_u32 s4, s4, 0x8000
	s_addc_u32 s5, s5, 0
	global_load_dwordx4 v[4:7], v64, s[4:5] nt
	s_add_u32 s4, s4, 0x8000
	s_addc_u32 s5, s5, 0
	global_load_dwordx4 v[8:11], v64, s[4:5] nt
	s_add_u32 s4, s4, 0x8000
	s_addc_u32 s5, s5, 0
	global_load_dwordx4 v[12:15], v64, s[4:5] nt
	s_add_u32 s4, s4, 0x8000
	s_addc_u32 s5, s5, 0
	global_load_dwordx4 v[16:19], v64, s[4:5] nt
	s_add_u32 s4, s4, 0x8000
	s_addc_u32 s5, s5, 0
	global_load_dwordx4 v[20:23], v64, s[4:5] nt
	s_add_u32 s4, s4, 0x8000
	s_addc_u32 s5, s5, 0
	global_load_dwordx4 v[24:27], v64, s[4:5] nt
	s_add_u32 s4, s4, 0x8000
	s_addc_u32 s5, s5, 0
	global_load_dwordx4 v[28:31], v64, s[4:5] nt
	s_add_u32 s4, s4, 0x8000
	s_addc_u32 s5, s5, 0
	global_load_dwordx4 v[32:35], v64, s[4:5] nt
	s_add_u32 s4, s4, 0x8000
	s_addc_u32 s5, s5, 0
	global_load_dwordx4 v[36:39], v64, s[4:5] nt
	s_add_u32 s4, s4, 0x8000
	s_addc_u32 s5, s5, 0
	global_load_dwordx4 v[40:43], v64, s[4:5] nt
	s_add_u32 s4, s4, 0x8000
	s_addc_u32 s5, s5, 0
	global_load_dwordx4 v[44:47], v64, s[4:5] nt
	s_add_u32 s4, s4, 0x8000
	s_addc_u32 s5, s5, 0
	global_load_dwordx4 v[48:51], v64, s[4:5] nt
	s_add_u32 s4, s4, 0x8000
	s_addc_u32 s5, s5, 0
	global_load_dwordx4 v[52:55], v64, s[4:5] nt
	s_add_u32 s4, s4, 0x8000
	s_addc_u32 s5, s5, 0
	global_load_dwordx4 v[56:59], v64, s[4:5] nt
	s_add_u32 s4, s4, 0x8000
	s_addc_u32 s5, s5, 0
	global_load_dwordx4 v[60:63], v64, s[4:5] nt
	s_waitcnt vmcnt(0)
	s_branch .Lcv_wde_body

.Lcv_wde_body:
	s_mov_b32 s22, s24
	s_mov_b32 s23, s25
	v_mov_b32_e32 v69, v65
	ds_write2_b32 v69, v0, v1 offset1:1
	ds_write2_b32 v69, v2, v3 offset0:2 offset1:3
	v_add_u32_e32 v69, 0x410, v69
	ds_write2_b32 v69, v4, v5 offset1:1
	ds_write2_b32 v69, v6, v7 offset0:2 offset1:3
	v_add_u32_e32 v69, 0x410, v69
	ds_write2_b32 v69, v8, v9 offset1:1
	ds_write2_b32 v69, v10, v11 offset0:2 offset1:3
	v_add_u32_e32 v69, 0x410, v69
	ds_write2_b32 v69, v12, v13 offset1:1
	ds_write2_b32 v69, v14, v15 offset0:2 offset1:3
	v_add_u32_e32 v69, 0x410, v69
	ds_write2_b32 v69, v16, v17 offset1:1
	ds_write2_b32 v69, v18, v19 offset0:2 offset1:3
	v_add_u32_e32 v69, 0x410, v69
	ds_write2_b32 v69, v20, v21 offset1:1
	ds_write2_b32 v69, v22, v23 offset0:2 offset1:3
	v_add_u32_e32 v69, 0x410, v69
	ds_write2_b32 v69, v24, v25 offset1:1
	ds_write2_b32 v69, v26, v27 offset0:2 offset1:3
	v_add_u32_e32 v69, 0x410, v69
	ds_write2_b32 v69, v28, v29 offset1:1
	ds_write2_b32 v69, v30, v31 offset0:2 offset1:3
	v_add_u32_e32 v69, 0x410, v69
	ds_write2_b32 v69, v32, v33 offset1:1
	ds_write2_b32 v69, v34, v35 offset0:2 offset1:3
	v_add_u32_e32 v69, 0x410, v69
	ds_write2_b32 v69, v36, v37 offset1:1
	ds_write2_b32 v69, v38, v39 offset0:2 offset1:3
	v_add_u32_e32 v69, 0x410, v69
	ds_write2_b32 v69, v40, v41 offset1:1
	ds_write2_b32 v69, v42, v43 offset0:2 offset1:3
	v_add_u32_e32 v69, 0x410, v69
	ds_write2_b32 v69, v44, v45 offset1:1
	ds_write2_b32 v69, v46, v47 offset0:2 offset1:3
	v_add_u32_e32 v69, 0x410, v69
	ds_write2_b32 v69, v48, v49 offset1:1
	ds_write2_b32 v69, v50, v51 offset0:2 offset1:3
	v_add_u32_e32 v69, 0x410, v69
	ds_write2_b32 v69, v52, v53 offset1:1
	ds_write2_b32 v69, v54, v55 offset0:2 offset1:3
	v_add_u32_e32 v69, 0x410, v69
	ds_write2_b32 v69, v56, v57 offset1:1
	ds_write2_b32 v69, v58, v59 offset0:2 offset1:3
	v_add_u32_e32 v69, 0x410, v69
	ds_write2_b32 v69, v60, v61 offset1:1
	ds_write2_b32 v69, v62, v63 offset0:2 offset1:3
	s_waitcnt lgkmcnt(0)
	s_addk_i32 s16, 0x400
	s_cmp_lt_u32 s16, 0x300
	s_cbranch_scc0 .Lcv_wde_noload
	s_lshr_b32 s98, s16, 5
	s_and_b32 s99, s16, 31
	s_lshl_b32 s0, s98, 19
	s_lshl_b32 s100, s99, 8
	s_add_u32 s0, s0, s100
	s_add_u32 s4, s18, s0
	s_addc_u32 s5, s19, 0
	s_mul_i32 s0, s99, 0xb0000
	s_lshl_b32 s100, s98, 7
	s_add_u32 s0, s0, s100
	s_add_u32 s24, s26, s0
	s_addc_u32 s25, s27, 0
	global_load_dwordx4 v[0:3], v64, s[4:5] nt
	s_add_u32 s4, s4, 0x8000
	s_addc_u32 s5, s5, 0
	global_load_dwordx4 v[4:7], v64, s[4:5] nt
	s_add_u32 s4, s4, 0x8000
	s_addc_u32 s5, s5, 0
	global_load_dwordx4 v[8:11], v64, s[4:5] nt
	s_add_u32 s4, s4, 0x8000
	s_addc_u32 s5, s5, 0
	global_load_dwordx4 v[12:15], v64, s[4:5] nt
	s_add_u32 s4, s4, 0x8000
	s_addc_u32 s5, s5, 0
	global_load_dwordx4 v[16:19], v64, s[4:5] nt
	s_add_u32 s4, s4, 0x8000
	s_addc_u32 s5, s5, 0
	global_load_dwordx4 v[20:23], v64, s[4:5] nt
	s_add_u32 s4, s4, 0x8000
	s_addc_u32 s5, s5, 0
	global_load_dwordx4 v[24:27], v64, s[4:5] nt
	s_add_u32 s4, s4, 0x8000
	s_addc_u32 s5, s5, 0
	global_load_dwordx4 v[28:31], v64, s[4:5] nt
	s_add_u32 s4, s4, 0x8000
	s_addc_u32 s5, s5, 0
	global_load_dwordx4 v[32:35], v64, s[4:5] nt
	s_add_u32 s4, s4, 0x8000
	s_addc_u32 s5, s5, 0
	global_load_dwordx4 v[36:39], v64, s[4:5] nt
	s_add_u32 s4, s4, 0x8000
	s_addc_u32 s5, s5, 0
	global_load_dwordx4 v[40:43], v64, s[4:5] nt
	s_add_u32 s4, s4, 0x8000
	s_addc_u32 s5, s5, 0
	global_load_dwordx4 v[44:47], v64, s[4:5] nt
	s_add_u32 s4, s4, 0x8000
	s_addc_u32 s5, s5, 0
	global_load_dwordx4 v[48:51], v64, s[4:5] nt
	s_add_u32 s4, s4, 0x8000
	s_addc_u32 s5, s5, 0
	global_load_dwordx4 v[52:55], v64, s[4:5] nt
	s_add_u32 s4, s4, 0x8000
	s_addc_u32 s5, s5, 0
	global_load_dwordx4 v[56:59], v64, s[4:5] nt
	s_add_u32 s4, s4, 0x8000
	s_addc_u32 s5, s5, 0
	global_load_dwordx4 v[60:63], v64, s[4:5] nt
.Lcv_wde_noload:
	s_mov_b32 s8, s22
	s_mov_b32 s9, s23
	ds_read2_b32 v[70:71], v66 offset0:0 offset1:8
	ds_read2_b32 v[72:73], v66 offset0:65 offset1:73
	ds_read2_b32 v[74:75], v66 offset0:130 offset1:138
	ds_read2_b32 v[76:77], v66 offset0:195 offset1:203
	ds_read2_b32 v[78:79], v67 offset0:0 offset1:8
	ds_read2_b32 v[80:81], v67 offset0:65 offset1:73
	ds_read2_b32 v[82:83], v67 offset0:130 offset1:138
	ds_read2_b32 v[84:85], v67 offset0:195 offset1:203
	ds_read2_b32 v[86:87], v66 offset0:16 offset1:24
	ds_read2_b32 v[88:89], v66 offset0:81 offset1:89
	ds_read2_b32 v[90:91], v66 offset0:146 offset1:154
	ds_read2_b32 v[92:93], v66 offset0:211 offset1:219
	ds_read2_b32 v[94:95], v67 offset0:16 offset1:24
	ds_read2_b32 v[96:97], v67 offset0:81 offset1:89
	ds_read2_b32 v[98:99], v67 offset0:146 offset1:154
	ds_read2_b32 v[100:101], v67 offset0:211 offset1:219
	s_waitcnt lgkmcnt(8)
	v_cvt_pk_bf16_f32 v102, v70, v72
	v_cvt_pk_bf16_f32 v103, v74, v76
	v_cvt_pk_bf16_f32 v104, v78, v80
	v_cvt_pk_bf16_f32 v105, v82, v84
	v_cvt_pk_bf16_f32 v106, v71, v73
	v_cvt_pk_bf16_f32 v107, v75, v77
	v_cvt_pk_bf16_f32 v108, v79, v81
	v_cvt_pk_bf16_f32 v109, v83, v85
	global_store_dwordx4 v68, v[102:105], s[8:9]
	s_add_u32 s8, s8, 0x16000
	s_addc_u32 s9, s9, 0
	global_store_dwordx4 v68, v[106:109], s[8:9]
	s_add_u32 s8, s8, 0x16000
	s_addc_u32 s9, s9, 0
	ds_read2_b32 v[70:71], v66 offset0:32 offset1:40
	ds_read2_b32 v[72:73], v66 offset0:97 offset1:105
	ds_read2_b32 v[74:75], v66 offset0:162 offset1:170
	ds_read2_b32 v[76:77], v66 offset0:227 offset1:235
	ds_read2_b32 v[78:79], v67 offset0:32 offset1:40
	ds_read2_b32 v[80:81], v67 offset0:97 offset1:105
	ds_read2_b32 v[82:83], v67 offset0:162 offset1:170
	ds_read2_b32 v[84:85], v67 offset0:227 offset1:235
	s_waitcnt lgkmcnt(8)
	v_cvt_pk_bf16_f32 v102, v86, v88
	v_cvt_pk_bf16_f32 v103, v90, v92
	v_cvt_pk_bf16_f32 v104, v94, v96
	v_cvt_pk_bf16_f32 v105, v98, v100
	v_cvt_pk_bf16_f32 v106, v87, v89
	v_cvt_pk_bf16_f32 v107, v91, v93
	v_cvt_pk_bf16_f32 v108, v95, v97
	v_cvt_pk_bf16_f32 v109, v99, v101
	global_store_dwordx4 v68, v[102:105], s[8:9]
	s_add_u32 s8, s8, 0x16000
	s_addc_u32 s9, s9, 0
	global_store_dwordx4 v68, v[106:109], s[8:9]
	s_add_u32 s8, s8, 0x16000
	s_addc_u32 s9, s9, 0
	ds_read2_b32 v[86:87], v66 offset0:48 offset1:56
	ds_read2_b32 v[88:89], v66 offset0:113 offset1:121
	ds_read2_b32 v[90:91], v66 offset0:178 offset1:186
	ds_read2_b32 v[92:93], v66 offset0:243 offset1:251
	ds_read2_b32 v[94:95], v67 offset0:48 offset1:56
	ds_read2_b32 v[96:97], v67 offset0:113 offset1:121
	ds_read2_b32 v[98:99], v67 offset0:178 offset1:186
	ds_read2_b32 v[100:101], v67 offset0:243 offset1:251
	s_waitcnt lgkmcnt(8)
	v_cvt_pk_bf16_f32 v102, v70, v72
	v_cvt_pk_bf16_f32 v103, v74, v76
	v_cvt_pk_bf16_f32 v104, v78, v80
	v_cvt_pk_bf16_f32 v105, v82, v84
	v_cvt_pk_bf16_f32 v106, v71, v73
	v_cvt_pk_bf16_f32 v107, v75, v77
	v_cvt_pk_bf16_f32 v108, v79, v81
	v_cvt_pk_bf16_f32 v109, v83, v85
	global_store_dwordx4 v68, v[102:105], s[8:9]
	s_add_u32 s8, s8, 0x16000
	s_addc_u32 s9, s9, 0
	global_store_dwordx4 v68, v[106:109], s[8:9]
	s_add_u32 s8, s8, 0x16000
	s_addc_u32 s9, s9, 0
	s_waitcnt lgkmcnt(0)
	v_cvt_pk_bf16_f32 v102, v86, v88
	v_cvt_pk_bf16_f32 v103, v90, v92
	v_cvt_pk_bf16_f32 v104, v94, v96
	v_cvt_pk_bf16_f32 v105, v98, v100
	v_cvt_pk_bf16_f32 v106, v87, v89
	v_cvt_pk_bf16_f32 v107, v91, v93
	v_cvt_pk_bf16_f32 v108, v95, v97
	v_cvt_pk_bf16_f32 v109, v99, v101
	global_store_dwordx4 v68, v[102:105], s[8:9]
	s_add_u32 s8, s8, 0x16000
	s_addc_u32 s9, s9, 0
	global_store_dwordx4 v68, v[106:109], s[8:9]
	s_cmp_lt_u32 s16, 0x300
	s_cbranch_scc1 .Lcv_wde_top
.Lcv_wde_skip:
	v_readlane_b32 s16, v111, 0
	v_readlane_b32 s17, v111, 1
	v_readlane_b32 s18, v111, 2
	v_readlane_b32 s19, v111, 3
	v_readlane_b32 s20, v111, 4
	v_readlane_b32 s21, v111, 5
	v_readlane_b32 s22, v111, 6
	v_readlane_b32 s23, v111, 7
	v_readlane_b32 s24, v111, 8
	v_readlane_b32 s25, v111, 9
	v_readlane_b32 s26, v111, 10
	v_readlane_b32 s27, v111, 11
	s_nop 4
	s_branch .LBB0_325
.LBB0_325:
	s_barrier

.LBB0_613:
	s_andn2_b64 vcc, exec, s[6:7]
	s_cbranch_vccnz .LBB0_618
	s_cmpk_gt_i32 s17, 0x7f
	s_cbranch_scc1 .LBB0_618
	v_and_b32_e32 v110, 63, v252
	v_lshrrev_b32_e32 v0, 6, v252
	v_writelane_b32 v111, s16, 0
	v_writelane_b32 v111, s17, 1
	v_writelane_b32 v111, s18, 2
	v_writelane_b32 v111, s19, 3
	v_writelane_b32 v111, s20, 4
	v_writelane_b32 v111, s21, 5
	v_writelane_b32 v111, s22, 6
	v_writelane_b32 v111, s23, 7
	v_writelane_b32 v111, s24, 8
	v_writelane_b32 v111, s25, 9
	v_writelane_b32 v111, s26, 10
	v_writelane_b32 v111, s27, 11
	v_readfirstlane_b32 s0, v0
	s_mul_i32 s1, s0, 0x4100
	s_lshl_b32 s16, s17, 3
	s_add_u32 s16, s16, s0
	s_add_u32 s16, s16, 0x300
	s_cmp_lt_u32 s16, 0xb00
	s_cbranch_scc0 .Lcv_wdl_skip
	v_lshrrev_b32_e32 v0, 4, v110
	v_and_b32_e32 v1, 15, v110
	v_and_b32_e32 v2, 7, v110
	v_lshrrev_b32_e32 v3, 3, v110
	v_mul_u32_u24_e32 v64, 0x2000, v0
	v_lshl_add_u32 v64, v1, 4, v64
	v_mul_u32_u24_e32 v65, 0x104, v0
	v_lshl_add_u32 v65, v1, 4, v65
	v_add_u32_e32 v65, s1, v65
	v_mul_u32_u24_e32 v66, 0x820, v2
	v_lshl_add_u32 v66, v3, 2, v66
	v_add_u32_e32 v66, s1, v66
	v_add_u32_e32 v67, 0x410, v66
	v_mul_u32_u24_e32 v68, 0x2c00, v3
	v_lshl_add_u32 v68, v2, 4, v68
	v_mov_b32_e32 v4, 0x23fa0
	ds_read_b64 v[0:1], v4
	s_waitcnt lgkmcnt(0)
	v_readfirstlane_b32 s18, v0
	v_readfirstlane_b32 s19, v1
	s_add_u32 s26, s54, 0x4800000
	s_addc_u32 s27, s55, 0
	s_nop 4
	s_lshr_b32 s98, s16, 5
	s_and_b32 s99, s16, 31
	s_lshl_b32 s0, s98, 19
	s_lshl_b32 s100, s99, 8
	s_add_u32 s0, s0, s100
	s_add_u32 s4, s18, s0
	s_addc_u32 s5, s19, 0
	s_mul_i32 s0, s99, 0xb0000
	s_lshl_b32 s100, s98, 7
	s_add_u32 s0, s0, s100
	s_add_u32 s24, s26, s0
	s_addc_u32 s25, s27, 0
	global_load_dwordx4 v[0:3], v64, s[4:5] nt
	s_add_u32 s4, s4, 0x8000
	s_addc_u32 s5, s5, 0
	global_load_dwordx4 v[4:7], v64, s[4:5] nt
	s_add_u32 s4, s4, 0x8000
	s_addc_u32 s5, s5, 0
	global_load_dwordx4 v[8:11], v64, s[4:5] nt
	s_add_u32 s4, s4, 0x8000
	s_addc_u32 s5, s5, 0
	global_load_dwordx4 v[12:15], v64, s[4:5] nt
	s_add_u32 s4, s4, 0x8000
	s_addc_u32 s5, s5, 0
	global_load_dwordx4 v[16:19], v64, s[4:5] nt
	s_add_u32 s4, s4, 0x8000
	s_addc_u32 s5, s5, 0
	global_load_dwordx4 v[20:23], v64, s[4:5] nt
	s_add_u32 s4, s4, 0x8000
	s_addc_u32 s5, s5, 0
	global_load_dwordx4 v[24:27], v64, s[4:5] nt
	s_add_u32 s4, s4, 0x8000
	s_addc_u32 s5, s5, 0
	global_load_dwordx4 v[28:31], v64, s[4:5] nt
	s_add_u32 s4, s4, 0x8000
	s_addc_u32 s5, s5, 0
	global_load_dwordx4 v[32:35], v64, s[4:5] nt
	s_add_u32 s4, s4, 0x8000
	s_addc_u32 s5, s5, 0
	global_load_dwordx4 v[36:39], v64, s[4:5] nt
	s_add_u32 s4, s4, 0x8000
	s_addc_u32 s5, s5, 0
	global_load_dwordx4 v[40:43], v64, s[4:5] nt
	s_add_u32 s4, s4, 0x8000
	s_addc_u32 s5, s5, 0
	global_load_dwordx4 v[44:47], v64, s[4:5] nt
	s_add_u32 s4, s4, 0x8000
	s_addc_u32 s5, s5, 0
	global_load_dwordx4 v[48:51], v64, s[4:5] nt
	s_add_u32 s4, s4, 0x8000
	s_addc_u32 s5, s5, 0
	global_load_dwordx4 v[52:55], v64, s[4:5] nt
	s_add_u32 s4, s4, 0x8000
	s_addc_u32 s5, s5, 0
	global_load_dwordx4 v[56:59], v64, s[4:5] nt
	s_add_u32 s4, s4, 0x8000
	s_addc_u32 s5, s5, 0
	global_load_dwordx4 v[60:63], v64, s[4:5] nt
	s_waitcnt vmcnt(0)
	s_branch .Lcv_wdl_body
